# P4 embedded conversion: the 4 serialized g_ffn gain loads per item issued together, one wait (was 4 dependent round trips)
# speedup vs baseline: 1.0058x; 1.0057x over previous
; #define GAS __attribute__((address_space(1)))
; #define LAS __attribute__((address_space(3)))
; #define LDS_WAIT() asm volatile("s_waitcnt lgkmcnt(0)" ::: "memory")
; __device__ __forceinline__ void conv_store(const ConvItem& it, int lane, const f32x4 (&v)[4], LAS bf16* scr) {
;     ...
;     const int c = lane & 3;
; #pragma unroll
;     for (int j = 0; j < 2; ++j) { const int n = (lane >> 2) + 16 * j; const LAS bf16* sp = scr + (8 * c) * 34 + n;
;         v4u o; o.x = (unsigned)sp[0] | ((unsigned)sp[34] << 16); o.y = (unsigned)sp[68] | ((unsigned)sp[102] << 16); o.z = (unsigned)sp[136] | ((unsigned)sp[170] << 16); o.w = (unsigned)sp[204] | ((unsigned)sp[238] << 16);
;         const int ng = it.n0 + n; const int row = it.rowmode == 0 ? ng : ((ng >> 7) * 256 + (it.rowmode == 2 ? 128 : 0) + (ng & 127));
;         __builtin_nontemporal_store(o, (GAS v4u*)(it.WT + (size_t)row * it.ldt + it.k0 + 8 * c)); }
;     LDS_WAIT(); asm volatile("" ::: "memory");
.Lcvj4:
	s_waitcnt lgkmcnt(0)
	ds_read_u16 v66, v167 offset:68
	ds_read_u16 v67, v167
	ds_read_u16 v74, v167 offset:32
	s_ashr_i32 s73, s72, 31
	s_lshl_b64 s[0:1], s[72:73], 1
	v_lshlrev_b32_e32 v116, 1, v122
	s_waitcnt lgkmcnt(1)
	v_lshl_or_b32 v70, v66, 16, v67
	ds_read_u16 v66, v167 offset:136
	ds_read_u16 v67, v167 offset:204
	s_waitcnt lgkmcnt(0)
	v_lshl_or_b32 v71, v67, 16, v66
	ds_read_u16 v66, v167 offset:272
	ds_read_u16 v67, v167 offset:340
	s_waitcnt lgkmcnt(0)
	v_lshl_or_b32 v72, v67, 16, v66
	ds_read_u16 v66, v167 offset:408
	ds_read_u16 v67, v167 offset:476
	s_waitcnt lgkmcnt(0)
	v_lshl_or_b32 v73, v67, 16, v66
	v_add_u32_e32 v66, s96, v166
	v_lshlrev_b32_e32 v67, 1, v66
	v_and_b32_e32 v75, 0x7f, v66
	v_and_or_b32 v67, v67, s45, v75
	v_cndmask_b32_e64 v66, v67, v66, s[94:95]
	v_ashrrev_i32_e32 v67, 31, v66
	v_lshlrev_b64 v[66:67], 13, v[66:67]
	v_lshl_add_u64 v[66:67], v[68:69], 0, v[66:67]
	v_lshl_add_u64 v[66:67], v[66:67], 0, s[0:1]
	v_lshl_add_u64 v[66:67], v[66:67], 0, v[116:117]
	global_store_dwordx4 v[66:67], v[70:73], off nt
	ds_read_u16 v66, v167 offset:100
	s_waitcnt lgkmcnt(0)
	v_lshl_or_b32 v70, v66, 16, v74
	ds_read_u16 v66, v167 offset:168
	ds_read_u16 v67, v167 offset:236
	s_waitcnt lgkmcnt(0)
	v_lshl_or_b32 v71, v67, 16, v66
	ds_read_u16 v66, v167 offset:304
	ds_read_u16 v67, v167 offset:372
	s_waitcnt lgkmcnt(0)
	v_lshl_or_b32 v72, v67, 16, v66
	ds_read_u16 v66, v167 offset:440
	ds_read_u16 v67, v167 offset:508
	s_waitcnt lgkmcnt(0)
	v_lshl_or_b32 v73, v67, 16, v66
	v_add_u32_e32 v66, s96, v168
	v_lshlrev_b32_e32 v67, 1, v66
	v_and_b32_e32 v74, 0x7f, v66
	v_and_or_b32 v67, v67, s45, v74
	v_cndmask_b32_e64 v66, v67, v66, s[94:95]
	v_ashrrev_i32_e32 v67, 31, v66
	v_lshlrev_b64 v[66:67], 13, v[66:67]
	v_lshl_add_u64 v[66:67], v[68:69], 0, v[66:67]
	v_lshl_add_u64 v[66:67], v[66:67], 0, s[0:1]
	v_lshl_add_u64 v[66:67], v[66:67], 0, v[116:117]
	global_store_dwordx4 v[66:67], v[70:73], off nt
	s_waitcnt lgkmcnt(0)

; __device__ __forceinline__ unsigned cvt_pk_bf16(float lo, float hi) { const cvt_f2 v = {lo, hi}; return __builtin_bit_cast(unsigned, __builtin_convertvector(v, cvt_b2)); }
; #define LAS __attribute__((address_space(3)))
; __device__ __forceinline__ float bf2f(unsigned short b) { return __uint_as_float(((unsigned)b) << 16); }
;     ...
; #pragma unroll
;             for (int tb = 0; tb < 2; ++tb) { float yv[4];
; #pragma unroll
;                 for (int r = 0; r < 4; ++r) { const int t = 16 * tb + 4 * q + r; const f32x4 p0 = *(const LAS f32x4*)(SSQ + t * 8), p1 = *(const LAS f32x4*)(SSQ + t * 8 + 4);
;                     const float tot = ((p0[0] + p0[1]) + (p0[2] + p0[3])) + ((p1[0] + p1[1]) + (p1[2] + p1[3])); const float rinv = __builtin_amdgcn_rsqf(tot * (1.0f / HD) + EPS);
;                     yv[r] = oacc[tb][r] * rinv * hn * bf2f(og[tb * 4 + r]); }
;                 const unsigned y01 = cvt_pk_bf16(yv[0], yv[1]), y23 = cvt_pk_bf16(yv[2], yv[3]); const int tq = 16 * tb + 4 * q, cv_ = 16 * w + fr;
;                 YT[tq * 128 + cv_] = (bf16)y01; YT[(tq + 1) * 128 + cv_] = (bf16)(y01 >> 16); YT[(tq + 2) * 128 + cv_] = (bf16)y23; YT[(tq + 3) * 128 + cv_] = (bf16)(y23 >> 16); }
.LBB0_588:
	s_or_b64 exec, exec, vcc
	v_add_u32_e32 v112, 0, v156
	v_add_u32_e32 v186, 0x13000, v112
	s_waitcnt lgkmcnt(0)
	s_barrier
	ds_read_b128 v[112:115], v186
	ds_read_b128 v[204:207], v186 offset:16
	ds_read_b128 v[208:211], v186 offset:32
	ds_read_b128 v[212:215], v186 offset:48
	v_lshlrev_b32_e32 v67, 16, v67
	s_waitcnt lgkmcnt(3)
	v_mov_b32_e32 v216, v112
	s_waitcnt lgkmcnt(2)
	v_mov_b32_e32 v217, v204
	v_mov_b32_e32 v204, v113
	v_pk_add_f32 v[112:113], v[216:217], v[204:205]
	v_mov_b32_e32 v204, v114
	v_mov_b32_e32 v205, v206
	v_mov_b32_e32 v206, v115
	v_pk_add_f32 v[114:115], v[204:205], v[206:207]
	v_lshlrev_b32_e32 v66, 16, v66
	v_pk_add_f32 v[112:113], v[112:113], v[114:115]
	s_waitcnt lgkmcnt(1)
	v_mov_b32_e32 v114, v210
	v_add_f32_e32 v112, v112, v113
	v_fmamk_f32 v112, v112, 0x3c000000, v170
	v_rsq_f32_e32 v216, v112
	v_mov_b32_e32 v112, v208
	s_waitcnt lgkmcnt(0)
	v_mov_b32_e32 v113, v212
	v_mov_b32_e32 v212, v209
	v_mov_b32_e32 v115, v214
	v_mov_b32_e32 v214, v211
	v_pk_add_f32 v[112:113], v[112:113], v[212:213]
	v_pk_add_f32 v[114:115], v[114:115], v[214:215]
	s_and_b64 vcc, exec, s[30:31]
	v_pk_add_f32 v[112:113], v[112:113], v[114:115]
	s_nop 0
	v_add_f32_e32 v112, v112, v113
	v_fmamk_f32 v112, v112, 0x3c000000, v170
	v_rsq_f32_e32 v217, v112
	ds_read_b128 v[112:115], v186 offset:64
	ds_read_b128 v[204:207], v186 offset:80
	v_pk_mul_f32 v[108:109], v[108:109], v[216:217]
	s_waitcnt lgkmcnt(1)
	v_mov_b32_e32 v208, v112
	s_waitcnt lgkmcnt(0)
	v_mov_b32_e32 v209, v204
	v_mov_b32_e32 v204, v113
	v_pk_add_f32 v[112:113], v[208:209], v[204:205]
	v_mov_b32_e32 v204, v114
	v_mov_b32_e32 v205, v206
	v_mov_b32_e32 v206, v115
	v_pk_add_f32 v[114:115], v[204:205], v[206:207]
	v_pk_mul_f32 v[108:109], v[130:131], v[108:109]
	v_pk_add_f32 v[208:209], v[112:113], v[114:115]
	ds_read_b128 v[112:115], v186 offset:96
	ds_read_b128 v[204:207], v186 offset:112
	v_add_f32_e32 v203, v208, v209
	v_fmamk_f32 v203, v203, 0x3c000000, v170
	v_rsq_f32_e32 v208, v203
	s_waitcnt lgkmcnt(1)
	v_mov_b32_e32 v210, v112
	s_waitcnt lgkmcnt(0)
	v_mov_b32_e32 v211, v204
	v_mov_b32_e32 v204, v113
	v_pk_add_f32 v[112:113], v[210:211], v[204:205]
	v_mov_b32_e32 v204, v114
	v_mov_b32_e32 v205, v206
	v_mov_b32_e32 v206, v115
	v_pk_add_f32 v[114:115], v[204:205], v[206:207]
	s_nop 0
	v_pk_add_f32 v[112:113], v[112:113], v[114:115]
	s_nop 0
	v_add_f32_e32 v112, v112, v113
	v_fmamk_f32 v112, v112, 0x3c000000, v170
	v_rsq_f32_e32 v209, v112
	v_lshlrev_b32_e32 v113, 16, v202
	v_lshlrev_b32_e32 v112, 16, v201
	v_pk_mul_f32 v[108:109], v[108:109], v[112:113]
	v_pk_mul_f32 v[110:111], v[110:111], v[208:209]
	v_lshlrev_b32_e32 v113, 16, v200
	v_pk_mul_f32 v[110:111], v[130:131], v[110:111]
	v_lshlrev_b32_e32 v112, 16, v199
	v_pk_mul_f32 v[110:111], v[110:111], v[112:113]
	v_cvt_pk_bf16_f32 v199, v108, v109
	v_cvt_pk_bf16_f32 v204, v110, v111
	ds_read_b128 v[108:111], v186 offset:512
	ds_read_b128 v[112:115], v186 offset:528
	ds_write_b16 v157, v199
	ds_write_b16_d16_hi v157, v199 offset:256
	ds_write_b16 v157, v204 offset:512
	s_waitcnt lgkmcnt(4)
	v_mov_b32_e32 v200, v108
	s_waitcnt lgkmcnt(3)
	v_mov_b32_e32 v201, v112
	v_mov_b32_e32 v112, v109
	v_pk_add_f32 v[108:109], v[200:201], v[112:113]
	v_mov_b32_e32 v112, v110
	v_mov_b32_e32 v113, v114
	v_mov_b32_e32 v114, v111
	v_pk_add_f32 v[110:111], v[112:113], v[114:115]
	s_nop 0
	v_pk_add_f32 v[200:201], v[108:109], v[110:111]
	ds_read_b128 v[108:111], v186 offset:544
	ds_read_b128 v[112:115], v186 offset:560
	v_add_f32_e32 v199, v200, v201
	v_fmamk_f32 v199, v199, 0x3c000000, v170
	v_rsq_f32_e32 v200, v199
	s_waitcnt lgkmcnt(1)
	v_mov_b32_e32 v202, v108
	s_waitcnt lgkmcnt(0)
	v_mov_b32_e32 v203, v112
	v_mov_b32_e32 v112, v109
	v_pk_add_f32 v[108:109], v[202:203], v[112:113]
	v_mov_b32_e32 v112, v110
	v_mov_b32_e32 v113, v114
	v_mov_b32_e32 v114, v111
	v_pk_add_f32 v[110:111], v[112:113], v[114:115]
	s_nop 0
	v_pk_add_f32 v[108:109], v[108:109], v[110:111]
	s_nop 0
	v_add_f32_e32 v108, v108, v109
	v_fmamk_f32 v108, v108, 0x3c000000, v170
	v_rsq_f32_e32 v201, v108
	ds_read_b128 v[108:111], v186 offset:576
	ds_read_b128 v[112:115], v186 offset:592
	ds_write_b16_d16_hi v157, v204 offset:768
	v_pk_mul_f32 v[104:105], v[104:105], v[200:201]
	s_waitcnt lgkmcnt(2)
	v_mov_b32_e32 v200, v108
	s_waitcnt lgkmcnt(1)
	v_mov_b32_e32 v201, v112
	v_mov_b32_e32 v112, v109
	v_pk_add_f32 v[108:109], v[200:201], v[112:113]
	v_mov_b32_e32 v112, v110
	v_mov_b32_e32 v113, v114
	v_mov_b32_e32 v114, v111
	v_pk_add_f32 v[110:111], v[112:113], v[114:115]
	v_pk_mul_f32 v[104:105], v[130:131], v[104:105]
	v_pk_add_f32 v[200:201], v[108:109], v[110:111]
	ds_read_b128 v[108:111], v186 offset:608
	ds_read_b128 v[112:115], v186 offset:624
	v_add_f32_e32 v199, v200, v201
	v_fmamk_f32 v199, v199, 0x3c000000, v170
	v_rsq_f32_e32 v200, v199
	s_waitcnt lgkmcnt(1)
	v_mov_b32_e32 v202, v108
	s_waitcnt lgkmcnt(0)
	v_mov_b32_e32 v203, v112
	v_mov_b32_e32 v112, v109
	v_pk_add_f32 v[108:109], v[202:203], v[112:113]
	v_mov_b32_e32 v112, v110
	v_mov_b32_e32 v113, v114
	v_mov_b32_e32 v114, v111
	v_pk_add_f32 v[110:111], v[112:113], v[114:115]
	s_nop 0
	v_pk_add_f32 v[108:109], v[108:109], v[110:111]
	s_nop 0
	v_add_f32_e32 v108, v108, v109
	v_fmamk_f32 v108, v108, 0x3c000000, v170
	v_rsq_f32_e32 v201, v108
	v_lshlrev_b32_e32 v109, 16, v198
	v_lshlrev_b32_e32 v108, 16, v116
	v_pk_mul_f32 v[104:105], v[104:105], v[108:109]
	v_pk_mul_f32 v[106:107], v[106:107], v[200:201]
	v_cvt_pk_bf16_f32 v104, v104, v105
	v_pk_mul_f32 v[106:107], v[130:131], v[106:107]
	s_nop 0
	v_pk_mul_f32 v[66:67], v[106:107], v[66:67]
	s_nop 0
	v_cvt_pk_bf16_f32 v66, v66, v67
	ds_write_b16 v157, v104 offset:4096
	ds_write_b16_d16_hi v157, v104 offset:4352
	ds_write_b16 v157, v66 offset:4608
	ds_write_b16_d16_hi v157, v66 offset:4864
	s_cbranch_vccnz .LBB0_596
; __device__ __forceinline__ unsigned cvt_pk_bf16(float lo, float hi) { const cvt_f2 v = {lo, hi}; return __builtin_bit_cast(unsigned, __builtin_convertvector(v, cvt_b2)); }
; #define LAS __attribute__((address_space(3)))
; #define LDS_WAIT() asm volatile("s_waitcnt lgkmcnt(0)" ::: "memory")
; __device__ __forceinline__ void conv_store(const ConvItem& it, int lane, const f32x4 (&v)[4], LAS bf16* scr) {
;     ...
; #pragma unroll
;     for (int i = 0; i < 4; ++i) { const float gk = it.kgain ? it.kgain[it.k0 + 8 * i + lk] : 1.0f; LAS unsigned* p = (LAS unsigned*)(scr + (8 * i + lk) * 34 + ln); p[0] = pg8::cvt_pk_bf16(v[i][0] * gk, v[i][1] * gk); p[1] = pg8::cvt_pk_bf16(v[i][2] * gk, v[i][3] * gk); }
;     LDS_WAIT(); asm volatile("" ::: "memory");
	v_cmp_eq_u64_e32 vcc, 0, v[140:141]
	v_cmp_ne_u64_e64 s[30:31], 0, v[140:141]
	s_cbranch_vccnz .LBB0_647
	v_add_u32_e32 v66, s36, v158
	v_ashrrev_i32_e32 v67, 31, v66
	v_lshl_add_u64 v[66:67], v[66:67], 2, v[140:141]
	flat_load_dword v246, v[66:67]
	v_add_u32_e32 v66, s36, v163
	v_ashrrev_i32_e32 v67, 31, v66
	v_lshl_add_u64 v[66:67], v[66:67], 2, v[140:141]
	flat_load_dword v248, v[66:67]
	v_add_u32_e32 v66, s36, v164
	v_ashrrev_i32_e32 v67, 31, v66
	v_lshl_add_u64 v[66:67], v[66:67], 2, v[140:141]
	flat_load_dword v250, v[66:67]
	v_add_u32_e32 v66, s36, v165
	v_ashrrev_i32_e32 v67, 31, v66
	v_lshl_add_u64 v[66:67], v[66:67], 2, v[140:141]
	flat_load_dword v252, v[66:67]
	s_waitcnt vmcnt(0) lgkmcnt(0)
	v_pk_mul_f32 v[104:105], v[100:101], v[246:247] op_sel_hi:[1,0]
	v_pk_mul_f32 v[66:67], v[102:103], v[246:247] op_sel_hi:[1,0]
	v_cvt_pk_bf16_f32 v104, v104, v105
	v_add_u32_e32 v105, v160, v161
	v_cvt_pk_bf16_f32 v66, v66, v67
	ds_write2_b32 v105, v104, v66 offset1:1
	v_pk_mul_f32 v[96:97], v[96:97], v[248:249] op_sel_hi:[1,0]
	v_pk_mul_f32 v[66:67], v[98:99], v[248:249] op_sel_hi:[1,0]
	v_cvt_pk_bf16_f32 v96, v96, v97
	v_add_u32_e32 v97, v160, v161
	v_cvt_pk_bf16_f32 v66, v66, v67
	ds_write2_b32 v97, v96, v66 offset0:136 offset1:137
	v_pk_mul_f32 v[96:97], v[92:93], v[250:251] op_sel_hi:[1,0]
	v_pk_mul_f32 v[66:67], v[94:95], v[250:251] op_sel_hi:[1,0]
	v_cvt_pk_bf16_f32 v96, v96, v97
	v_add3_u32 v97, v160, v161, s83
	v_cvt_pk_bf16_f32 v66, v66, v67
	ds_write2_b32 v97, v96, v66 offset1:1
	v_pk_mul_f32 v[88:89], v[88:89], v[252:253] op_sel_hi:[1,0]
	v_pk_mul_f32 v[66:67], v[90:91], v[252:253] op_sel_hi:[1,0]
	v_cvt_pk_bf16_f32 v88, v88, v89
	v_add3_u32 v89, v160, v161, s44
	v_cvt_pk_bf16_f32 v66, v66, v67
	ds_write2_b32 v89, v88, v66 offset1:1
	s_branch .Lcvj1

; __device__ __forceinline__ unsigned cvt_pk_bf16(float lo, float hi) { const cvt_f2 v = {lo, hi}; return __builtin_bit_cast(unsigned, __builtin_convertvector(v, cvt_b2)); }
; #define GAS __attribute__((address_space(1)))
; #define LAS __attribute__((address_space(3)))
; #define LDS_WAIT() asm volatile("s_waitcnt lgkmcnt(0)" ::: "memory")
; __device__ __forceinline__ void conv_store(const ConvItem& it, int lane, const f32x4 (&v)[4], LAS bf16* scr) {
;     ...
; #pragma unroll
;     for (int i = 0; i < 4; ++i) { const float gk = it.kgain ? it.kgain[it.k0 + 8 * i + lk] : 1.0f; LAS unsigned* p = (LAS unsigned*)(scr + (8 * i + lk) * 34 + ln); p[0] = pg8::cvt_pk_bf16(v[i][0] * gk, v[i][1] * gk); p[1] = pg8::cvt_pk_bf16(v[i][2] * gk, v[i][3] * gk); }
;     LDS_WAIT(); asm volatile("" ::: "memory");
;     const int c = lane & 3;
; #pragma unroll
;     for (int j = 0; j < 2; ++j) { const int n = (lane >> 2) + 16 * j; const LAS bf16* sp = scr + (8 * c) * 34 + n;
;         v4u o; o.x = (unsigned)sp[0] | ((unsigned)sp[34] << 16); o.y = (unsigned)sp[68] | ((unsigned)sp[102] << 16); o.z = (unsigned)sp[136] | ((unsigned)sp[170] << 16); o.w = (unsigned)sp[204] | ((unsigned)sp[238] << 16);
;         const int ng = it.n0 + n; const int row = it.rowmode == 0 ? ng : ((ng >> 7) * 256 + (it.rowmode == 2 ? 128 : 0) + (ng & 127));
;         __builtin_nontemporal_store(o, (GAS v4u*)(it.WT + (size_t)row * it.ldt + it.k0 + 8 * c)); }
;     LDS_WAIT(); asm volatile("" ::: "memory");
.Lcvj1:
	s_waitcnt lgkmcnt(0)
	ds_read_u16 v66, v167 offset:68
	ds_read_u16 v67, v167
	ds_read_u16 v92, v167 offset:32
	s_ashr_i32 s37, s36, 31
	s_lshl_b64 s[30:31], s[36:37], 1
	v_lshlrev_b32_e32 v116, 1, v122
	s_waitcnt lgkmcnt(1)
	v_lshl_or_b32 v88, v66, 16, v67
	ds_read_u16 v66, v167 offset:136
	ds_read_u16 v67, v167 offset:204
	s_waitcnt lgkmcnt(0)
	v_lshl_or_b32 v89, v67, 16, v66
	ds_read_u16 v66, v167 offset:272
	ds_read_u16 v67, v167 offset:340
	s_waitcnt lgkmcnt(0)
	v_lshl_or_b32 v90, v67, 16, v66
	ds_read_u16 v66, v167 offset:408
	ds_read_u16 v67, v167 offset:476
	s_waitcnt lgkmcnt(0)
	v_lshl_or_b32 v91, v67, 16, v66
	v_add_u32_e32 v66, s72, v166
	v_lshlrev_b32_e32 v67, 1, v66
	v_and_b32_e32 v93, 0x7f, v66
	v_and_or_b32 v67, v67, s45, v93
	v_cndmask_b32_e64 v66, v67, v66, s[76:77]
	v_ashrrev_i32_e32 v67, 31, v66
	v_lshlrev_b64 v[66:67], 13, v[66:67]
	v_lshl_add_u64 v[66:67], v[70:71], 0, v[66:67]
	v_lshl_add_u64 v[66:67], v[66:67], 0, s[30:31]
	v_lshl_add_u64 v[66:67], v[66:67], 0, v[116:117]
	global_store_dwordx4 v[66:67], v[88:91], off nt
	ds_read_u16 v66, v167 offset:100
	s_waitcnt lgkmcnt(0)
	v_lshl_or_b32 v88, v66, 16, v92
	ds_read_u16 v66, v167 offset:168
	ds_read_u16 v67, v167 offset:236
	s_waitcnt lgkmcnt(0)
	v_lshl_or_b32 v89, v67, 16, v66
	ds_read_u16 v66, v167 offset:304
	ds_read_u16 v67, v167 offset:372
	s_waitcnt lgkmcnt(0)
	v_lshl_or_b32 v90, v67, 16, v66
	ds_read_u16 v66, v167 offset:440
	ds_read_u16 v67, v167 offset:508
	s_waitcnt lgkmcnt(0)
	v_lshl_or_b32 v91, v67, 16, v66
	v_add_u32_e32 v66, s72, v168
	v_lshlrev_b32_e32 v67, 1, v66
	v_and_b32_e32 v92, 0x7f, v66
	v_and_or_b32 v67, v67, s45, v92
	v_cndmask_b32_e64 v66, v67, v66, s[76:77]
	v_ashrrev_i32_e32 v67, 31, v66
	v_lshlrev_b64 v[66:67], 13, v[66:67]
	v_lshl_add_u64 v[66:67], v[70:71], 0, v[66:67]
	v_lshl_add_u64 v[66:67], v[66:67], 0, s[30:31]
	v_lshl_add_u64 v[66:67], v[66:67], 0, v[116:117]
	global_store_dwordx4 v[66:67], v[88:91], off nt
	s_waitcnt lgkmcnt(0)
.LBB0_596:
	s_and_b64 vcc, exec, s[28:29]
	s_cbranch_vccnz .LBB0_604
	v_cmp_eq_u64_e32 vcc, 0, v[138:139]
	v_cmp_ne_u64_e64 s[28:29], 0, v[138:139]
	s_cbranch_vccnz .LBB0_649
	v_add_u32_e32 v66, s0, v158
	v_ashrrev_i32_e32 v67, 31, v66
	v_lshl_add_u64 v[66:67], v[66:67], 2, v[138:139]
	flat_load_dword v246, v[66:67]
	v_add_u32_e32 v66, s0, v163
	v_ashrrev_i32_e32 v67, 31, v66
	v_lshl_add_u64 v[66:67], v[66:67], 2, v[138:139]
	flat_load_dword v248, v[66:67]
	v_add_u32_e32 v66, s0, v164
	v_ashrrev_i32_e32 v67, 31, v66
	v_lshl_add_u64 v[66:67], v[66:67], 2, v[138:139]
	flat_load_dword v250, v[66:67]
	v_add_u32_e32 v66, s0, v165
	v_ashrrev_i32_e32 v67, 31, v66
	v_lshl_add_u64 v[66:67], v[66:67], 2, v[138:139]
	flat_load_dword v252, v[66:67]
	s_waitcnt vmcnt(0) lgkmcnt(0)
	v_pk_mul_f32 v[70:71], v[84:85], v[246:247] op_sel_hi:[1,0]
	v_pk_mul_f32 v[66:67], v[86:87], v[246:247] op_sel_hi:[1,0]
	v_cvt_pk_bf16_f32 v70, v70, v71
	v_add_u32_e32 v71, v160, v161
	v_cvt_pk_bf16_f32 v66, v66, v67
	ds_write2_b32 v71, v70, v66 offset1:1
	v_pk_mul_f32 v[70:71], v[80:81], v[248:249] op_sel_hi:[1,0]
	v_pk_mul_f32 v[66:67], v[82:83], v[248:249] op_sel_hi:[1,0]
	v_cvt_pk_bf16_f32 v70, v70, v71
	v_add_u32_e32 v71, v160, v161
	v_cvt_pk_bf16_f32 v66, v66, v67
	ds_write2_b32 v71, v70, v66 offset0:136 offset1:137
	v_pk_mul_f32 v[70:71], v[76:77], v[250:251] op_sel_hi:[1,0]
	v_pk_mul_f32 v[66:67], v[78:79], v[250:251] op_sel_hi:[1,0]
	v_cvt_pk_bf16_f32 v70, v70, v71
	v_add3_u32 v71, v160, v161, s83
	v_cvt_pk_bf16_f32 v66, v66, v67
	ds_write2_b32 v71, v70, v66 offset1:1
	v_pk_mul_f32 v[70:71], v[72:73], v[252:253] op_sel_hi:[1,0]
	v_pk_mul_f32 v[66:67], v[74:75], v[252:253] op_sel_hi:[1,0]
	v_cvt_pk_bf16_f32 v70, v70, v71
	v_add3_u32 v71, v160, v161, s44
	v_cvt_pk_bf16_f32 v66, v66, v67
	ds_write2_b32 v71, v70, v66 offset1:1
	s_branch .Lcvj2

; #define GAS __attribute__((address_space(1)))
; #define LAS __attribute__((address_space(3)))
; #define LDS_WAIT() asm volatile("s_waitcnt lgkmcnt(0)" ::: "memory")
; __device__ __forceinline__ void conv_store(const ConvItem& it, int lane, const f32x4 (&v)[4], LAS bf16* scr) {
;     ...
;     const int c = lane & 3;
; #pragma unroll
;     for (int j = 0; j < 2; ++j) { const int n = (lane >> 2) + 16 * j; const LAS bf16* sp = scr + (8 * c) * 34 + n;
;         v4u o; o.x = (unsigned)sp[0] | ((unsigned)sp[34] << 16); o.y = (unsigned)sp[68] | ((unsigned)sp[102] << 16); o.z = (unsigned)sp[136] | ((unsigned)sp[170] << 16); o.w = (unsigned)sp[204] | ((unsigned)sp[238] << 16);
;         const int ng = it.n0 + n; const int row = it.rowmode == 0 ? ng : ((ng >> 7) * 256 + (it.rowmode == 2 ? 128 : 0) + (ng & 127));
;         __builtin_nontemporal_store(o, (GAS v4u*)(it.WT + (size_t)row * it.ldt + it.k0 + 8 * c)); }
;     LDS_WAIT(); asm volatile("" ::: "memory");
.Lcvj2:
	s_waitcnt lgkmcnt(0)
	ds_read_u16 v66, v167 offset:68
	ds_read_u16 v67, v167
	ds_read_u16 v74, v167 offset:32
	s_ashr_i32 s1, s0, 31
	s_lshl_b64 s[0:1], s[0:1], 1
	v_lshlrev_b32_e32 v116, 1, v122
	s_waitcnt lgkmcnt(1)
	v_lshl_or_b32 v70, v66, 16, v67
	ds_read_u16 v66, v167 offset:136
	ds_read_u16 v67, v167 offset:204
	s_waitcnt lgkmcnt(0)
	v_lshl_or_b32 v71, v67, 16, v66
	ds_read_u16 v66, v167 offset:272
	ds_read_u16 v67, v167 offset:340
	s_waitcnt lgkmcnt(0)
	v_lshl_or_b32 v72, v67, 16, v66
	ds_read_u16 v66, v167 offset:408
	ds_read_u16 v67, v167 offset:476
	s_waitcnt lgkmcnt(0)
	v_lshl_or_b32 v73, v67, 16, v66
	v_add_u32_e32 v66, s96, v166
	v_lshlrev_b32_e32 v67, 1, v66
	v_and_b32_e32 v75, 0x7f, v66
	v_and_or_b32 v67, v67, s45, v75
	v_cndmask_b32_e64 v66, v67, v66, s[94:95]
	v_ashrrev_i32_e32 v67, 31, v66
	v_lshlrev_b64 v[66:67], 13, v[66:67]
	v_lshl_add_u64 v[66:67], v[68:69], 0, v[66:67]
	v_lshl_add_u64 v[66:67], v[66:67], 0, s[0:1]
	v_lshl_add_u64 v[66:67], v[66:67], 0, v[116:117]
	global_store_dwordx4 v[66:67], v[70:73], off nt
	ds_read_u16 v66, v167 offset:100
	s_waitcnt lgkmcnt(0)
	v_lshl_or_b32 v70, v66, 16, v74
	ds_read_u16 v66, v167 offset:168
	ds_read_u16 v67, v167 offset:236
	s_waitcnt lgkmcnt(0)
	v_lshl_or_b32 v71, v67, 16, v66
	ds_read_u16 v66, v167 offset:304
	ds_read_u16 v67, v167 offset:372
	s_waitcnt lgkmcnt(0)
	v_lshl_or_b32 v72, v67, 16, v66
	ds_read_u16 v66, v167 offset:440
	ds_read_u16 v67, v167 offset:508
	s_waitcnt lgkmcnt(0)
	v_lshl_or_b32 v73, v67, 16, v66
	v_add_u32_e32 v66, s96, v168
	v_lshlrev_b32_e32 v67, 1, v66
	v_and_b32_e32 v74, 0x7f, v66
	v_and_or_b32 v67, v67, s45, v74
	v_cndmask_b32_e64 v66, v67, v66, s[94:95]
	v_ashrrev_i32_e32 v67, 31, v66
	v_lshlrev_b64 v[66:67], 13, v[66:67]
	v_lshl_add_u64 v[66:67], v[68:69], 0, v[66:67]
	v_lshl_add_u64 v[66:67], v[66:67], 0, s[0:1]
	v_lshl_add_u64 v[66:67], v[66:67], 0, v[116:117]
	global_store_dwordx4 v[66:67], v[70:73], off nt
	s_waitcnt lgkmcnt(0)

; __device__ __forceinline__ unsigned cvt_pk_bf16(float lo, float hi) { const cvt_f2 v = {lo, hi}; return __builtin_bit_cast(unsigned, __builtin_convertvector(v, cvt_b2)); }
; #define LAS __attribute__((address_space(3)))
; __device__ __forceinline__ float bf2f(unsigned short b) { return __uint_as_float(((unsigned)b) << 16); }
;     ...
;             for (int tb = 0; tb < 2; ++tb) { float yv[4];
; #pragma unroll
;                 for (int r = 0; r < 4; ++r) { const int t = 16 * tb + 4 * q + r; const f32x4 p0 = *(const LAS f32x4*)(SSQ + t * 8), p1 = *(const LAS f32x4*)(SSQ + t * 8 + 4);
;                     const float tot = ((p0[0] + p0[1]) + (p0[2] + p0[3])) + ((p1[0] + p1[1]) + (p1[2] + p1[3])); const float rinv = __builtin_amdgcn_rsqf(tot * (1.0f / HD) + EPS);
;                     yv[r] = oacc[tb][r] * rinv * hn * bf2f(og[tb * 4 + r]); }
;                 const unsigned y01 = cvt_pk_bf16(yv[0], yv[1]), y23 = cvt_pk_bf16(yv[2], yv[3]); const int tq = 16 * tb + 4 * q, cv_ = 16 * w + fr;
;                 YT[tq * 128 + cv_] = (bf16)y01; YT[(tq + 1) * 128 + cv_] = (bf16)(y01 >> 16); YT[(tq + 2) * 128 + cv_] = (bf16)y23; YT[(tq + 3) * 128 + cv_] = (bf16)(y23 >> 16); }
.LBB0_633:
	s_or_b64 exec, exec, s[26:27]
	s_waitcnt lgkmcnt(0)
	s_barrier
	ds_read_b128 v[112:115], v186
	ds_read_b128 v[188:191], v186 offset:16
	ds_read_b128 v[192:195], v186 offset:32
	ds_read_b128 v[202:205], v186 offset:48
	v_lshlrev_b32_e32 v67, 16, v67
	s_waitcnt lgkmcnt(3)
	v_mov_b32_e32 v196, v112
	s_waitcnt lgkmcnt(2)
	v_mov_b32_e32 v197, v188
	v_mov_b32_e32 v188, v113
	v_pk_add_f32 v[112:113], v[196:197], v[188:189]
	v_mov_b32_e32 v188, v114
	v_mov_b32_e32 v189, v190
	v_mov_b32_e32 v190, v115
	v_pk_add_f32 v[114:115], v[188:189], v[190:191]
	v_lshlrev_b32_e32 v66, 16, v66
	v_pk_add_f32 v[112:113], v[112:113], v[114:115]
	s_waitcnt lgkmcnt(1)
	v_mov_b32_e32 v114, v194
	v_add_f32_e32 v112, v112, v113
	v_fmamk_f32 v112, v112, 0x3c000000, v170
	v_rsq_f32_e32 v196, v112
	v_mov_b32_e32 v112, v192
	s_waitcnt lgkmcnt(0)
	v_mov_b32_e32 v113, v202
	v_mov_b32_e32 v202, v193
	v_mov_b32_e32 v115, v204
	v_mov_b32_e32 v204, v195
	v_pk_add_f32 v[112:113], v[112:113], v[202:203]
	v_pk_add_f32 v[114:115], v[114:115], v[204:205]
	s_and_b64 vcc, exec, s[30:31]
	v_pk_add_f32 v[112:113], v[112:113], v[114:115]
	s_nop 0
	v_add_f32_e32 v112, v112, v113
	v_fmamk_f32 v112, v112, 0x3c000000, v170
	v_rsq_f32_e32 v197, v112
	ds_read_b128 v[112:115], v186 offset:64
	ds_read_b128 v[188:191], v186 offset:80
	v_pk_mul_f32 v[108:109], v[108:109], v[196:197]
	s_waitcnt lgkmcnt(1)
	v_mov_b32_e32 v192, v112
	s_waitcnt lgkmcnt(0)
	v_mov_b32_e32 v193, v188
	v_mov_b32_e32 v188, v113
	v_pk_add_f32 v[112:113], v[192:193], v[188:189]
	v_mov_b32_e32 v188, v114
	v_mov_b32_e32 v189, v190
	v_mov_b32_e32 v190, v115
	v_pk_add_f32 v[114:115], v[188:189], v[190:191]
	v_pk_mul_f32 v[108:109], v[130:131], v[108:109]
	v_pk_add_f32 v[192:193], v[112:113], v[114:115]
	ds_read_b128 v[112:115], v186 offset:96
	ds_read_b128 v[188:191], v186 offset:112
	v_add_f32_e32 v192, v192, v193
	v_fmamk_f32 v192, v192, 0x3c000000, v170
	v_rsq_f32_e32 v192, v192
	s_waitcnt lgkmcnt(1)
	v_mov_b32_e32 v194, v112
	s_waitcnt lgkmcnt(0)
	v_mov_b32_e32 v195, v188
	v_mov_b32_e32 v188, v113
	v_pk_add_f32 v[112:113], v[194:195], v[188:189]
	v_mov_b32_e32 v188, v114
	v_mov_b32_e32 v189, v190
	v_mov_b32_e32 v190, v115
	v_pk_add_f32 v[114:115], v[188:189], v[190:191]
	s_nop 0
	v_pk_add_f32 v[112:113], v[112:113], v[114:115]
	s_nop 0
	v_add_f32_e32 v112, v112, v113
	v_fmamk_f32 v112, v112, 0x3c000000, v170
	v_rsq_f32_e32 v193, v112
	v_lshlrev_b32_e32 v113, 16, v201
	v_lshlrev_b32_e32 v112, 16, v200
	v_pk_mul_f32 v[108:109], v[108:109], v[112:113]
	v_pk_mul_f32 v[110:111], v[110:111], v[192:193]
	v_lshlrev_b32_e32 v113, 16, v199
	v_pk_mul_f32 v[110:111], v[130:131], v[110:111]
	v_lshlrev_b32_e32 v112, 16, v198
	v_pk_mul_f32 v[110:111], v[110:111], v[112:113]
	v_cvt_pk_bf16_f32 v188, v108, v109
	v_cvt_pk_bf16_f32 v192, v110, v111
	ds_read_b128 v[108:111], v186 offset:512
	ds_read_b128 v[112:115], v186 offset:528
	ds_write_b16 v157, v188
	ds_write_b16_d16_hi v157, v188 offset:256
	ds_write_b16 v157, v192 offset:512
	s_waitcnt lgkmcnt(4)
	v_mov_b32_e32 v188, v108
	s_waitcnt lgkmcnt(3)
	v_mov_b32_e32 v189, v112
	v_mov_b32_e32 v112, v109
	v_pk_add_f32 v[108:109], v[188:189], v[112:113]
	v_mov_b32_e32 v112, v110
	v_mov_b32_e32 v113, v114
	v_mov_b32_e32 v114, v111
	v_pk_add_f32 v[110:111], v[112:113], v[114:115]
	s_nop 0
	v_pk_add_f32 v[188:189], v[108:109], v[110:111]
	ds_read_b128 v[108:111], v186 offset:544
	ds_read_b128 v[112:115], v186 offset:560
	v_add_f32_e32 v188, v188, v189
	v_fmamk_f32 v188, v188, 0x3c000000, v170
	v_rsq_f32_e32 v188, v188
	s_waitcnt lgkmcnt(1)
	v_mov_b32_e32 v190, v108
	s_waitcnt lgkmcnt(0)
	v_mov_b32_e32 v191, v112
	v_mov_b32_e32 v112, v109
	v_pk_add_f32 v[108:109], v[190:191], v[112:113]
	v_mov_b32_e32 v112, v110
	v_mov_b32_e32 v113, v114
	v_mov_b32_e32 v114, v111
	v_pk_add_f32 v[110:111], v[112:113], v[114:115]
	s_nop 0
	v_pk_add_f32 v[108:109], v[108:109], v[110:111]
	s_nop 0
	v_add_f32_e32 v108, v108, v109
	v_fmamk_f32 v108, v108, 0x3c000000, v170
	v_rsq_f32_e32 v189, v108
	ds_read_b128 v[108:111], v186 offset:576
	ds_read_b128 v[112:115], v186 offset:592
	ds_write_b16_d16_hi v157, v192 offset:768
	v_pk_mul_f32 v[104:105], v[104:105], v[188:189]
	s_waitcnt lgkmcnt(2)
	v_mov_b32_e32 v188, v108
	s_waitcnt lgkmcnt(1)
	v_mov_b32_e32 v189, v112
	v_mov_b32_e32 v112, v109
	v_pk_add_f32 v[108:109], v[188:189], v[112:113]
	v_mov_b32_e32 v112, v110
	v_mov_b32_e32 v113, v114
	v_mov_b32_e32 v114, v111
	v_pk_add_f32 v[110:111], v[112:113], v[114:115]
	v_pk_mul_f32 v[104:105], v[130:131], v[104:105]
	v_pk_add_f32 v[188:189], v[108:109], v[110:111]
	ds_read_b128 v[108:111], v186 offset:608
	ds_read_b128 v[112:115], v186 offset:624
	v_add_f32_e32 v186, v188, v189
	v_fmamk_f32 v186, v186, 0x3c000000, v170
	v_rsq_f32_e32 v188, v186
	s_waitcnt lgkmcnt(1)
	v_mov_b32_e32 v190, v108
	s_waitcnt lgkmcnt(0)
	v_mov_b32_e32 v191, v112
	v_mov_b32_e32 v112, v109
	v_pk_add_f32 v[108:109], v[190:191], v[112:113]
	v_mov_b32_e32 v112, v110
	v_mov_b32_e32 v113, v114
	v_mov_b32_e32 v114, v111
	v_pk_add_f32 v[110:111], v[112:113], v[114:115]
	s_nop 0
	v_pk_add_f32 v[108:109], v[108:109], v[110:111]
	s_nop 0
	v_add_f32_e32 v108, v108, v109
	v_fmamk_f32 v108, v108, 0x3c000000, v170
	v_rsq_f32_e32 v189, v108
	v_lshlrev_b32_e32 v109, 16, v187
	v_lshlrev_b32_e32 v108, 16, v116
	v_pk_mul_f32 v[104:105], v[104:105], v[108:109]
	v_pk_mul_f32 v[106:107], v[106:107], v[188:189]
	v_cvt_pk_bf16_f32 v104, v104, v105
	v_pk_mul_f32 v[106:107], v[130:131], v[106:107]
	s_nop 0
	v_pk_mul_f32 v[66:67], v[106:107], v[66:67]
	s_nop 0
	v_cvt_pk_bf16_f32 v66, v66, v67
	ds_write_b16 v157, v104 offset:4096
	ds_write_b16_d16_hi v157, v104 offset:4352
	ds_write_b16 v157, v66 offset:4608
	ds_write_b16_d16_hi v157, v66 offset:4864
	s_cbranch_vccnz .LBB0_641
; __device__ __forceinline__ unsigned cvt_pk_bf16(float lo, float hi) { const cvt_f2 v = {lo, hi}; return __builtin_bit_cast(unsigned, __builtin_convertvector(v, cvt_b2)); }
; #define LAS __attribute__((address_space(3)))
; __device__ __forceinline__ void conv_store(const ConvItem& it, int lane, const f32x4 (&v)[4], LAS bf16* scr) {
;     const int lk = lane >> 3, ln = (lane & 7) * 4;
; #pragma unroll
;     for (int i = 0; i < 4; ++i) { const float gk = it.kgain ? it.kgain[it.k0 + 8 * i + lk] : 1.0f; LAS unsigned* p = (LAS unsigned*)(scr + (8 * i + lk) * 34 + ln); p[0] = pg8::cvt_pk_bf16(v[i][0] * gk, v[i][1] * gk); p[1] = pg8::cvt_pk_bf16(v[i][2] * gk, v[i][3] * gk); }
	v_cmp_eq_u64_e32 vcc, 0, v[140:141]
	v_cmp_ne_u64_e64 s[26:27], 0, v[140:141]
	s_cbranch_vccnz .LBB0_651
	v_add_u32_e32 v66, s36, v158
	v_ashrrev_i32_e32 v67, 31, v66
	v_lshl_add_u64 v[66:67], v[66:67], 2, v[140:141]
	flat_load_dword v246, v[66:67]
	v_add_u32_e32 v66, s36, v163
	v_ashrrev_i32_e32 v67, 31, v66
	v_lshl_add_u64 v[66:67], v[66:67], 2, v[140:141]
	flat_load_dword v248, v[66:67]
	v_add_u32_e32 v66, s36, v164
	v_ashrrev_i32_e32 v67, 31, v66
	v_lshl_add_u64 v[66:67], v[66:67], 2, v[140:141]
	flat_load_dword v250, v[66:67]
	v_add_u32_e32 v66, s36, v165
	v_ashrrev_i32_e32 v67, 31, v66
	v_lshl_add_u64 v[66:67], v[66:67], 2, v[140:141]
	flat_load_dword v252, v[66:67]
	s_waitcnt vmcnt(0) lgkmcnt(0)
	v_pk_mul_f32 v[104:105], v[100:101], v[246:247] op_sel_hi:[1,0]
	v_pk_mul_f32 v[66:67], v[102:103], v[246:247] op_sel_hi:[1,0]
	v_cvt_pk_bf16_f32 v104, v104, v105
	v_add_u32_e32 v105, v160, v161
	v_cvt_pk_bf16_f32 v66, v66, v67
	ds_write2_b32 v105, v104, v66 offset1:1
	v_pk_mul_f32 v[96:97], v[96:97], v[248:249] op_sel_hi:[1,0]
	v_pk_mul_f32 v[66:67], v[98:99], v[248:249] op_sel_hi:[1,0]
	v_cvt_pk_bf16_f32 v96, v96, v97
	v_add_u32_e32 v97, v160, v161
	v_cvt_pk_bf16_f32 v66, v66, v67
	ds_write2_b32 v97, v96, v66 offset0:136 offset1:137
	v_pk_mul_f32 v[96:97], v[92:93], v[250:251] op_sel_hi:[1,0]
	v_pk_mul_f32 v[66:67], v[94:95], v[250:251] op_sel_hi:[1,0]
	v_cvt_pk_bf16_f32 v96, v96, v97
	v_add3_u32 v97, v160, v161, s83
	v_cvt_pk_bf16_f32 v66, v66, v67
	ds_write2_b32 v97, v96, v66 offset1:1
	v_pk_mul_f32 v[88:89], v[88:89], v[252:253] op_sel_hi:[1,0]
	v_pk_mul_f32 v[66:67], v[90:91], v[252:253] op_sel_hi:[1,0]
	v_cvt_pk_bf16_f32 v88, v88, v89
	v_add3_u32 v89, v160, v161, s44
	v_cvt_pk_bf16_f32 v66, v66, v67
	ds_write2_b32 v89, v88, v66 offset1:1
	s_branch .Lcvj3

; __device__ __forceinline__ unsigned cvt_pk_bf16(float lo, float hi) { const cvt_f2 v = {lo, hi}; return __builtin_bit_cast(unsigned, __builtin_convertvector(v, cvt_b2)); }
; #define GAS __attribute__((address_space(1)))
; #define LAS __attribute__((address_space(3)))
; #define LDS_WAIT() asm volatile("s_waitcnt lgkmcnt(0)" ::: "memory")
; __device__ __forceinline__ void conv_store(const ConvItem& it, int lane, const f32x4 (&v)[4], LAS bf16* scr) {
;     ...
;     for (int i = 0; i < 4; ++i) { const float gk = it.kgain ? it.kgain[it.k0 + 8 * i + lk] : 1.0f; LAS unsigned* p = (LAS unsigned*)(scr + (8 * i + lk) * 34 + ln); p[0] = pg8::cvt_pk_bf16(v[i][0] * gk, v[i][1] * gk); p[1] = pg8::cvt_pk_bf16(v[i][2] * gk, v[i][3] * gk); }
;     LDS_WAIT(); asm volatile("" ::: "memory");
;     const int c = lane & 3;
; #pragma unroll
;     for (int j = 0; j < 2; ++j) { const int n = (lane >> 2) + 16 * j; const LAS bf16* sp = scr + (8 * c) * 34 + n;
;         v4u o; o.x = (unsigned)sp[0] | ((unsigned)sp[34] << 16); o.y = (unsigned)sp[68] | ((unsigned)sp[102] << 16); o.z = (unsigned)sp[136] | ((unsigned)sp[170] << 16); o.w = (unsigned)sp[204] | ((unsigned)sp[238] << 16);
;         const int ng = it.n0 + n; const int row = it.rowmode == 0 ? ng : ((ng >> 7) * 256 + (it.rowmode == 2 ? 128 : 0) + (ng & 127));
;         __builtin_nontemporal_store(o, (GAS v4u*)(it.WT + (size_t)row * it.ldt + it.k0 + 8 * c)); }
;     LDS_WAIT(); asm volatile("" ::: "memory");
.Lcvj3:
	s_waitcnt lgkmcnt(0)
	ds_read_u16 v66, v167 offset:68
	ds_read_u16 v67, v167
	ds_read_u16 v92, v167 offset:32
	s_ashr_i32 s37, s36, 31
	s_lshl_b64 s[26:27], s[36:37], 1
	v_lshlrev_b32_e32 v116, 1, v122
	s_waitcnt lgkmcnt(1)
	v_lshl_or_b32 v88, v66, 16, v67
	ds_read_u16 v66, v167 offset:136
	ds_read_u16 v67, v167 offset:204
	s_waitcnt lgkmcnt(0)
	v_lshl_or_b32 v89, v67, 16, v66
	ds_read_u16 v66, v167 offset:272
	ds_read_u16 v67, v167 offset:340
	s_waitcnt lgkmcnt(0)
	v_lshl_or_b32 v90, v67, 16, v66
	ds_read_u16 v66, v167 offset:408
	ds_read_u16 v67, v167 offset:476
	s_waitcnt lgkmcnt(0)
	v_lshl_or_b32 v91, v67, 16, v66
	v_add_u32_e32 v66, s76, v166
	v_lshlrev_b32_e32 v67, 1, v66
	v_and_b32_e32 v93, 0x7f, v66
	v_and_or_b32 v67, v67, s45, v93
	v_cndmask_b32_e64 v66, v67, v66, s[0:1]
	v_ashrrev_i32_e32 v67, 31, v66
	v_lshlrev_b64 v[66:67], 13, v[66:67]
	v_lshl_add_u64 v[66:67], v[70:71], 0, v[66:67]
	v_lshl_add_u64 v[66:67], v[66:67], 0, s[26:27]
	v_lshl_add_u64 v[66:67], v[66:67], 0, v[116:117]
	global_store_dwordx4 v[66:67], v[88:91], off nt
	ds_read_u16 v66, v167 offset:100
	s_waitcnt lgkmcnt(0)
	v_lshl_or_b32 v88, v66, 16, v92
	ds_read_u16 v66, v167 offset:168
	ds_read_u16 v67, v167 offset:236
	s_waitcnt lgkmcnt(0)
	v_lshl_or_b32 v89, v67, 16, v66
	ds_read_u16 v66, v167 offset:304
	ds_read_u16 v67, v167 offset:372
	s_waitcnt lgkmcnt(0)
	v_lshl_or_b32 v90, v67, 16, v66
	ds_read_u16 v66, v167 offset:440
	ds_read_u16 v67, v167 offset:508
	s_waitcnt lgkmcnt(0)
	v_lshl_or_b32 v91, v67, 16, v66
	v_add_u32_e32 v66, s76, v168
	v_lshlrev_b32_e32 v67, 1, v66
	v_and_b32_e32 v92, 0x7f, v66
	v_and_or_b32 v67, v67, s45, v92
	v_cndmask_b32_e64 v66, v67, v66, s[0:1]
	v_ashrrev_i32_e32 v67, 31, v66
	v_lshlrev_b64 v[66:67], 13, v[66:67]
	v_lshl_add_u64 v[66:67], v[70:71], 0, v[66:67]
	v_lshl_add_u64 v[66:67], v[66:67], 0, s[26:27]
	v_lshl_add_u64 v[66:67], v[66:67], 0, v[116:117]
	global_store_dwordx4 v[66:67], v[88:91], off nt
	s_waitcnt lgkmcnt(0)
.LBB0_641:
	s_and_b64 vcc, exec, s[28:29]
	s_cbranch_vccnz .LBB0_557
	v_cmp_eq_u64_e32 vcc, 0, v[138:139]
	v_cmp_ne_u64_e64 s[26:27], 0, v[138:139]
	v_add_u32_e32 v67, v160, v161
	s_cbranch_vccnz .LBB0_653
	v_add_u32_e32 v70, s72, v158
	v_ashrrev_i32_e32 v71, 31, v70
	v_lshl_add_u64 v[70:71], v[70:71], 2, v[138:139]
	flat_load_dword v246, v[70:71]
	v_add_u32_e32 v70, s72, v163
	v_ashrrev_i32_e32 v71, 31, v70
	v_lshl_add_u64 v[70:71], v[70:71], 2, v[138:139]
	flat_load_dword v248, v[70:71]
	v_add_u32_e32 v70, s72, v164
	v_ashrrev_i32_e32 v71, 31, v70
	v_lshl_add_u64 v[70:71], v[70:71], 2, v[138:139]
	flat_load_dword v250, v[70:71]
	v_add_u32_e32 v70, s72, v165
	v_ashrrev_i32_e32 v71, 31, v70
	v_lshl_add_u64 v[70:71], v[70:71], 2, v[138:139]
	flat_load_dword v252, v[70:71]
	s_waitcnt vmcnt(0) lgkmcnt(0)
	v_pk_mul_f32 v[70:71], v[84:85], v[246:247] op_sel_hi:[1,0]
	v_pk_mul_f32 v[88:89], v[86:87], v[246:247] op_sel_hi:[1,0]
	v_cvt_pk_bf16_f32 v70, v70, v71
	s_nop 0
	v_cvt_pk_bf16_f32 v66, v88, v89
	ds_write2_b32 v67, v70, v66 offset1:1
	v_pk_mul_f32 v[70:71], v[80:81], v[248:249] op_sel_hi:[1,0]
	v_pk_mul_f32 v[88:89], v[82:83], v[248:249] op_sel_hi:[1,0]
	v_cvt_pk_bf16_f32 v70, v70, v71
	s_nop 0
	v_cvt_pk_bf16_f32 v66, v88, v89
	ds_write2_b32 v67, v70, v66 offset0:136 offset1:137
	v_pk_mul_f32 v[70:71], v[76:77], v[250:251] op_sel_hi:[1,0]
	v_pk_mul_f32 v[88:89], v[78:79], v[250:251] op_sel_hi:[1,0]
	v_cvt_pk_bf16_f32 v70, v70, v71
	v_add3_u32 v67, v160, v161, s83
	v_cvt_pk_bf16_f32 v66, v88, v89
	ds_write2_b32 v67, v70, v66 offset1:1
	v_pk_mul_f32 v[70:71], v[72:73], v[252:253] op_sel_hi:[1,0]
	v_pk_mul_f32 v[88:89], v[74:75], v[252:253] op_sel_hi:[1,0]
	v_cvt_pk_bf16_f32 v70, v70, v71
	v_add3_u32 v71, v160, v161, s44
	v_cvt_pk_bf16_f32 v66, v88, v89
	ds_write2_b32 v71, v70, v66 offset1:1
	s_branch .Lcvj4

; __global__ void __launch_bounds__(NWAVES * 64, 2) fwd(Args args) {
	.amdhsa_kernel _Z3fwd4Args
		.amdhsa_group_segment_fixed_size 0
		.amdhsa_private_segment_fixed_size 0
		.amdhsa_kernarg_size 408
		.amdhsa_user_sgpr_count 2
		.amdhsa_user_sgpr_dispatch_ptr 0
		.amdhsa_user_sgpr_queue_ptr 0
		.amdhsa_user_sgpr_kernarg_segment_ptr 1
		.amdhsa_user_sgpr_dispatch_id 0
		.amdhsa_user_sgpr_kernarg_preload_length 0
		.amdhsa_user_sgpr_kernarg_preload_offset 0
		.amdhsa_user_sgpr_private_segment_size 0
		.amdhsa_uses_dynamic_stack 0
		.amdhsa_enable_private_segment 0
		.amdhsa_system_sgpr_workgroup_id_x 1
		.amdhsa_system_sgpr_workgroup_id_y 0
		.amdhsa_system_sgpr_workgroup_id_z 0
		.amdhsa_system_sgpr_workgroup_info 0
		.amdhsa_system_vgpr_workitem_id 0
		.amdhsa_next_free_vgpr 254
		.amdhsa_next_free_sgpr 98
		.amdhsa_accum_offset 256
		.amdhsa_reserve_vcc 1
		.amdhsa_float_round_mode_32 0
		.amdhsa_float_round_mode_16_64 0
		.amdhsa_float_denorm_mode_32 3
		.amdhsa_float_denorm_mode_16_64 3
		.amdhsa_dx10_clamp 1
		.amdhsa_ieee_mode 1
		.amdhsa_fp16_overflow 0
		.amdhsa_tg_split 0
		.amdhsa_exception_fp_ieee_invalid_op 0
		.amdhsa_exception_fp_denorm_src 0
		.amdhsa_exception_fp_ieee_div_zero 0
		.amdhsa_exception_fp_ieee_overflow 0
		.amdhsa_exception_fp_ieee_underflow 0
		.amdhsa_exception_fp_ieee_inexact 0
		.amdhsa_exception_int_div_zero 0
	.end_amdhsa_kernel

; __global__ void __launch_bounds__(NWAVES * 64, 2) fwd(Args args) {
amdhsa.kernels:
  - .agpr_count:     0
    .args:
      - .offset:         0
        .size:           152
        .value_kind:     by_value
      - .offset:         152
        .size:           4
        .value_kind:     hidden_block_count_x
      - .offset:         156
        .size:           4
        .value_kind:     hidden_block_count_y
      - .offset:         160
        .size:           4
        .value_kind:     hidden_block_count_z
      - .offset:         164
        .size:           2
        .value_kind:     hidden_group_size_x
      - .offset:         166
        .size:           2
        .value_kind:     hidden_group_size_y
      - .offset:         168
        .size:           2
        .value_kind:     hidden_group_size_z
      - .offset:         170
        .size:           2
        .value_kind:     hidden_remainder_x
      - .offset:         172
        .size:           2
        .value_kind:     hidden_remainder_y
      - .offset:         174
        .size:           2
        .value_kind:     hidden_remainder_z
      - .offset:         192
        .size:           8
        .value_kind:     hidden_global_offset_x
      - .offset:         200
        .size:           8
        .value_kind:     hidden_global_offset_y
      - .offset:         208
        .size:           8
        .value_kind:     hidden_global_offset_z
      - .offset:         216
        .size:           2
        .value_kind:     hidden_grid_dims
      - .offset:         272
        .size:           4
        .value_kind:     hidden_dynamic_lds_size
    .group_segment_fixed_size: 0
    .kernarg_segment_align: 8
    .kernarg_segment_size: 408
    .language:       OpenCL C
    .language_version:
      - 2
      - 0
    .max_flat_workgroup_size: 512
    .name:           _Z3fwd4Args
    .private_segment_fixed_size: 0
    .sgpr_count:     104
    .sgpr_spill_count: 22
    .symbol:         _Z3fwd4Args.kd
    .uniform_work_group_size: 1
    .uses_dynamic_stack: false
    .vgpr_count:     254
    .vgpr_spill_count: 0
    .wavefront_size: 64
